# attention epilogues: row-per-lane dwordx2 stores widened to dwordx4 via v_permlane32_swap (ATT1 common exit + GQA epilogue)
# speedup vs baseline: 1.0210x; 1.0015x over previous
.LBB0_687:
	v_div_scale_f32 v33, s[0:1], v32, v32, 1.0
	v_rcp_f32_e32 v34, v33
	v_div_scale_f32 v35, vcc, 1.0, v32, 1.0
	v_readlane_b32 s0, v251, 4
	v_fma_f32 v36, -v33, v34, 1.0
	v_fmac_f32_e32 v34, v36, v34
	v_mul_f32_e32 v36, v35, v34
	v_fma_f32 v37, -v33, v36, v35
	v_fmac_f32_e32 v36, v37, v34
	v_fma_f32 v33, -v33, v36, v35
	v_div_fmas_f32 v33, v33, v34, v36
	v_div_fixup_f32 v32, v33, v32, 1.0
	v_lshl_add_u64 v[36:37], v[130:131], 2, v[88:89]
	v_pk_mul_f32 v[0:1], v[0:1], v[32:33] op_sel_hi:[1,0]
	v_pk_mul_f32 v[2:3], v[2:3], v[32:33] op_sel_hi:[1,0]
	v_pk_mul_f32 v[4:5], v[4:5], v[32:33] op_sel_hi:[1,0]
	v_pk_mul_f32 v[6:7], v[6:7], v[32:33] op_sel_hi:[1,0]
	v_cvt_pk_bf16_f32 v0, v0, v1
	v_cvt_pk_bf16_f32 v1, v2, v3
	v_cvt_pk_bf16_f32 v2, v4, v5
	v_cvt_pk_bf16_f32 v3, v6, v7
	s_nop 1
	v_permlane32_swap_b32_e32 v0, v2
	v_permlane32_swap_b32_e32 v1, v3
	global_store_dwordx4 v[36:37], v[0:3], off
	v_pk_mul_f32 v[8:9], v[8:9], v[32:33] op_sel_hi:[1,0]
	v_pk_mul_f32 v[10:11], v[10:11], v[32:33] op_sel_hi:[1,0]
	v_pk_mul_f32 v[12:13], v[12:13], v[32:33] op_sel_hi:[1,0]
	v_pk_mul_f32 v[14:15], v[14:15], v[32:33] op_sel_hi:[1,0]
	v_cvt_pk_bf16_f32 v8, v8, v9
	v_cvt_pk_bf16_f32 v9, v10, v11
	v_cvt_pk_bf16_f32 v10, v12, v13
	v_cvt_pk_bf16_f32 v11, v14, v15
	s_nop 1
	v_permlane32_swap_b32_e32 v8, v10
	v_permlane32_swap_b32_e32 v9, v11
	global_store_dwordx4 v[36:37], v[8:11], off offset:32
	v_pk_mul_f32 v[16:17], v[16:17], v[32:33] op_sel_hi:[1,0]
	v_pk_mul_f32 v[18:19], v[18:19], v[32:33] op_sel_hi:[1,0]
	v_pk_mul_f32 v[20:21], v[20:21], v[32:33] op_sel_hi:[1,0]
	v_pk_mul_f32 v[22:23], v[22:23], v[32:33] op_sel_hi:[1,0]
	v_cvt_pk_bf16_f32 v16, v16, v17
	v_cvt_pk_bf16_f32 v17, v18, v19
	v_cvt_pk_bf16_f32 v18, v20, v21
	v_cvt_pk_bf16_f32 v19, v22, v23
	s_nop 1
	v_permlane32_swap_b32_e32 v16, v18
	v_permlane32_swap_b32_e32 v17, v19
	global_store_dwordx4 v[36:37], v[16:19], off offset:64
	v_pk_mul_f32 v[24:25], v[24:25], v[32:33] op_sel_hi:[1,0]
	v_pk_mul_f32 v[26:27], v[26:27], v[32:33] op_sel_hi:[1,0]
	v_pk_mul_f32 v[28:29], v[28:29], v[32:33] op_sel_hi:[1,0]
	v_pk_mul_f32 v[30:31], v[30:31], v[32:33] op_sel_hi:[1,0]
	v_cvt_pk_bf16_f32 v24, v24, v25
	v_cvt_pk_bf16_f32 v25, v26, v27
	v_cvt_pk_bf16_f32 v26, v28, v29
	v_cvt_pk_bf16_f32 v27, v30, v31
	s_nop 1
	v_permlane32_swap_b32_e32 v24, v26
	v_permlane32_swap_b32_e32 v25, v27
	global_store_dwordx4 v[36:37], v[24:27], off offset:96
	v_readlane_b32 s1, v251, 5
	s_load_dword s0, s[0:1], 0x10
	s_waitcnt lgkmcnt(0)
	s_lshr_b32 s0, s0, 16
	s_cmp_lg_u32 s0, 0
	s_cselect_b64 s[0:1], -1, 0
	s_cmp_lg_u64 s[0:1], 0
	v_readlane_b32 s0, v251, 0
	s_addc_u32 s20, s20, s0
	s_cmpk_lt_i32 s20, 0xa00
	v_readlane_b32 s1, v251, 1
	s_cbranch_scc0 .LBB0_674

.LBB0_1175:
	s_waitcnt vmcnt(0)
	s_nop 11
	v_mov_b32_e32 v32, v232
	v_div_scale_f32 v33, s[0:1], v32, v32, 1.0
	v_rcp_f32_e32 v34, v33
	v_mov_b32_e32 v91, v131
	v_fma_f32 v35, -v33, v34, 1.0
	v_fmac_f32_e32 v34, v35, v34
	v_div_scale_f32 v35, vcc, 1.0, v32, 1.0
	v_mul_f32_e32 v36, v35, v34
	v_fma_f32 v37, -v33, v36, v35
	v_fmac_f32_e32 v36, v37, v34
	v_fma_f32 v33, -v33, v36, v35
	v_div_fmas_f32 v33, v33, v34, v36
	v_div_fixup_f32 v32, v33, v32, 1.0
	s_barrier
	v_lshlrev_b32_e32 v36, 1, v90
	v_mov_b32_e32 v37, 0
	v_lshl_add_u64 v[36:37], v[88:89], 0, v[36:37]
	v_pk_mul_f32 v[0:1], v[0:1], v[32:33] op_sel_hi:[1,0]
	v_pk_mul_f32 v[2:3], v[2:3], v[32:33] op_sel_hi:[1,0]
	v_pk_mul_f32 v[4:5], v[4:5], v[32:33] op_sel_hi:[1,0]
	v_pk_mul_f32 v[6:7], v[6:7], v[32:33] op_sel_hi:[1,0]
	v_cvt_pk_bf16_f32 v0, v0, v1
	v_cvt_pk_bf16_f32 v1, v2, v3
	v_cvt_pk_bf16_f32 v2, v4, v5
	v_cvt_pk_bf16_f32 v3, v6, v7
	s_nop 1
	v_permlane32_swap_b32_e32 v0, v2
	v_permlane32_swap_b32_e32 v1, v3
	global_store_dwordx4 v[36:37], v[0:3], off
	v_pk_mul_f32 v[8:9], v[8:9], v[32:33] op_sel_hi:[1,0]
	v_pk_mul_f32 v[10:11], v[10:11], v[32:33] op_sel_hi:[1,0]
	v_pk_mul_f32 v[12:13], v[12:13], v[32:33] op_sel_hi:[1,0]
	v_pk_mul_f32 v[14:15], v[14:15], v[32:33] op_sel_hi:[1,0]
	v_cvt_pk_bf16_f32 v8, v8, v9
	v_cvt_pk_bf16_f32 v9, v10, v11
	v_cvt_pk_bf16_f32 v10, v12, v13
	v_cvt_pk_bf16_f32 v11, v14, v15
	s_nop 1
	v_permlane32_swap_b32_e32 v8, v10
	v_permlane32_swap_b32_e32 v9, v11
	global_store_dwordx4 v[36:37], v[8:11], off offset:32
	v_pk_mul_f32 v[16:17], v[16:17], v[32:33] op_sel_hi:[1,0]
	v_pk_mul_f32 v[18:19], v[18:19], v[32:33] op_sel_hi:[1,0]
	v_pk_mul_f32 v[20:21], v[20:21], v[32:33] op_sel_hi:[1,0]
	v_pk_mul_f32 v[22:23], v[22:23], v[32:33] op_sel_hi:[1,0]
	v_cvt_pk_bf16_f32 v16, v16, v17
	v_cvt_pk_bf16_f32 v17, v18, v19
	v_cvt_pk_bf16_f32 v18, v20, v21
	v_cvt_pk_bf16_f32 v19, v22, v23
	s_nop 1
	v_permlane32_swap_b32_e32 v16, v18
	v_permlane32_swap_b32_e32 v17, v19
	global_store_dwordx4 v[36:37], v[16:19], off offset:64
	v_pk_mul_f32 v[24:25], v[24:25], v[32:33] op_sel_hi:[1,0]
	v_pk_mul_f32 v[26:27], v[26:27], v[32:33] op_sel_hi:[1,0]
	v_pk_mul_f32 v[28:29], v[28:29], v[32:33] op_sel_hi:[1,0]
	v_pk_mul_f32 v[30:31], v[30:31], v[32:33] op_sel_hi:[1,0]
	v_cvt_pk_bf16_f32 v24, v24, v25
	v_cvt_pk_bf16_f32 v25, v26, v27
	v_cvt_pk_bf16_f32 v26, v28, v29
	v_cvt_pk_bf16_f32 v27, v30, v31
	s_nop 1
	v_permlane32_swap_b32_e32 v24, v26
	v_permlane32_swap_b32_e32 v25, v27
	global_store_dwordx4 v[36:37], v[24:27], off offset:96
